# group-local barriers (one counter per bx%8 group, no L2 write-back) at the nine XCD-local seams, guarded by a runtime XCC-consistency census; on top of peel + plain stores
# speedup vs baseline: 1.0281x; 1.0254x over previous
_Z14fwd_megakernel4Args:
	s_load_dwordx8 s[36:43], s[0:1], 0x80
	s_load_dword s3, s[0:1], 0xa8
	s_load_dwordx2 s[14:15], s[0:1], 0xa0
	s_add_u32 s6, s0, 0xa0
	v_and_b32_e32 v241, 0x3ff, v0
	s_addc_u32 s7, s1, 0
	v_cmp_gt_u32_e32 vcc, 64, v241
	s_and_saveexec_b64 s[4:5], vcc
	v_lshl_add_u32 v1, v241, 2, 0
	v_add_u32_e32 v1, 0x20000, v1
	v_mov_b32_e32 v2, 0
	ds_write_b32 v1, v2
	s_or_b64 exec, exec, s[4:5]
	s_waitcnt lgkmcnt(0)
	s_barrier
	s_add_u32 s34, s42, 0xe0000
	s_getreg_b32 s4, hwreg(HW_REG_XCC_ID, 0, 4)
	s_addc_u32 s35, s43, 0
	s_and_b32 s52, s4, 15
	v_cmp_eq_u32_e64 s[62:63], 0, v241
	s_and_saveexec_b64 s[4:5], s[62:63]
	s_cbranch_execz .LBB0_5
	s_mov_b64 s[8:9], exec
	v_mbcnt_lo_u32_b32 v1, s8, 0
	v_mbcnt_hi_u32_b32 v1, s9, v1
	v_cmp_eq_u32_e32 vcc, 0, v1
	s_and_b64 s[10:11], exec, vcc
	s_mov_b64 exec, s[10:11]
	s_cbranch_execz .LBB0_5
	s_lshl_b32 s10, s52, 8
	s_bcnt1_i32_b64 s8, s[8:9]
	v_mov_b32_e32 v1, s10
	v_mov_b32_e32 v2, s8
	global_atomic_add v1, v2, s[34:35] offset:1024
	s_and_b32 s12, s2, 7
	s_lshl_b32 s12, s12, 3
	s_add_u32 s12, s12, 0x3800
	s_add_i32 s13, s52, 1
	v_mov_b32_e32 v3, s12
	v_mov_b32_e32 v4, s13
	s_sub_i32 s13, 16, s52
	v_mov_b32_e32 v5, s13
	global_atomic_umax v3, v4, s[34:35]
	global_atomic_umax v3, v5, s[34:35] offset:4

.LBB0_172:
	v_writelane_b32 v252, s54, 49
	s_nop 1
	v_writelane_b32 v252, s55, 50
	s_or_b64 exec, exec, s[0:1]
	v_writelane_b32 v252, s60, 51
	s_add_i32 s6, s30, s87
	s_add_u32 s0, s42, 0x200000
	v_writelane_b32 v252, s61, 52
	v_writelane_b32 v252, s0, 53
	s_addc_u32 s0, s43, 0
	v_writelane_b32 v252, s0, 54
	s_add_u32 s0, s42, 0x100000
	v_writelane_b32 v252, s0, 55
	s_addc_u32 s0, s43, 0
	s_abs_i32 s50, s30
	s_waitcnt lgkmcnt(0)
	v_cvt_f32_u32_e32 v0, s50
	v_writelane_b32 v252, s0, 56
	s_sub_i32 s0, 0, s50
	s_mov_b32 s7, s30
	v_rcp_iflag_f32_e32 v0, v0
	s_mov_b32 s11, 0
	v_mov_b32_e32 v129, 0
	s_ashr_i32 s33, s30, 31
	v_mul_f32_e32 v0, 0x4f7ffffe, v0
	v_cvt_u32_f32_e32 v0, v0
	s_mov_b64 s[12:13], 0x20000
	s_mov_b64 s[14:15], 0x40000
	s_mov_b64 s[16:17], 0x60000
	v_readfirstlane_b32 s1, v0
	s_mul_i32 s0, s0, s1
	s_mul_hi_u32 s0, s1, s0
	s_add_i32 s51, s1, s0
	s_add_i32 s0, 0, 0x20100
	s_mov_b64 s[18:19], 0x80
	s_mov_b64 s[20:21], 0x20080
	s_mov_b64 s[22:23], 0x40080
	s_mov_b64 s[24:25], 0x60080
	v_writelane_b32 v252, s0, 57
	v_mov_b32_e32 v143, 1.0
	v_mov_b32_e32 v144, 1
	s_mov_b32 s54, 0
	s_barrier
	s_mov_b32 s100, 0
	v_readlane_b32 s0, v252, 34
	v_readlane_b32 s56, v252, 45
	v_readlane_b32 s57, v252, 46
	s_cmp_lg_u32 s0, 0x100
	s_cbranch_scc1 .Llbf_done
	s_add_u32 s56, s56, 0xe3800
	s_addc_u32 s57, s57, 0
	v_and_b32_e32 v0, 63, v241
	v_lshlrev_b32_e32 v0, 2, v0
	s_nop 1
	global_load_dword v1, v0, s[56:57] sc1
	s_waitcnt vmcnt(0)
	s_mov_b32 s10, 1
	v_readlane_b32 s4, v1, 0
	v_readlane_b32 s5, v1, 1
	s_nop 0
	s_add_i32 s5, s4, s5
	s_cmp_eq_u32 s5, 17
	s_cselect_b32 s10, s10, 0
	s_cmp_lg_u32 s4, 0
	s_cselect_b32 s10, s10, 0
	v_readlane_b32 s4, v1, 2
	v_readlane_b32 s5, v1, 3
	s_nop 0
	s_add_i32 s5, s4, s5
	s_cmp_eq_u32 s5, 17
	s_cselect_b32 s10, s10, 0
	s_cmp_lg_u32 s4, 0
	s_cselect_b32 s10, s10, 0
	v_readlane_b32 s4, v1, 4
	v_readlane_b32 s5, v1, 5
	s_nop 0
	s_add_i32 s5, s4, s5
	s_cmp_eq_u32 s5, 17
	s_cselect_b32 s10, s10, 0
	s_cmp_lg_u32 s4, 0
	s_cselect_b32 s10, s10, 0
	v_readlane_b32 s4, v1, 6
	v_readlane_b32 s5, v1, 7
	s_nop 0
	s_add_i32 s5, s4, s5
	s_cmp_eq_u32 s5, 17
	s_cselect_b32 s10, s10, 0
	s_cmp_lg_u32 s4, 0
	s_cselect_b32 s10, s10, 0
	v_readlane_b32 s4, v1, 8
	v_readlane_b32 s5, v1, 9
	s_nop 0
	s_add_i32 s5, s4, s5
	s_cmp_eq_u32 s5, 17
	s_cselect_b32 s10, s10, 0
	s_cmp_lg_u32 s4, 0
	s_cselect_b32 s10, s10, 0
	v_readlane_b32 s4, v1, 10
	v_readlane_b32 s5, v1, 11
	s_nop 0
	s_add_i32 s5, s4, s5
	s_cmp_eq_u32 s5, 17
	s_cselect_b32 s10, s10, 0
	s_cmp_lg_u32 s4, 0
	s_cselect_b32 s10, s10, 0
	v_readlane_b32 s4, v1, 12
	v_readlane_b32 s5, v1, 13
	s_nop 0
	s_add_i32 s5, s4, s5
	s_cmp_eq_u32 s5, 17
	s_cselect_b32 s10, s10, 0
	s_cmp_lg_u32 s4, 0
	s_cselect_b32 s10, s10, 0
	v_readlane_b32 s4, v1, 14
	v_readlane_b32 s5, v1, 15
	s_nop 0
	s_add_i32 s5, s4, s5
	s_cmp_eq_u32 s5, 17
	s_cselect_b32 s10, s10, 0
	s_cmp_lg_u32 s4, 0
	s_cselect_b32 s10, s10, 0
	s_mov_b32 s100, s10

.LBB0_515:
	s_waitcnt vmcnt(0)
	s_waitcnt vmcnt(0) lgkmcnt(0)
	s_barrier
	s_and_saveexec_b64 s[0:1], s[62:63]
	s_cbranch_execz .LBB0_202
	v_readlane_b32 s8, v254, 49
	s_mov_b32 s9, 0x19f3
	s_nop 0
	s_lshr_b32 s12, s9, s8
	s_and_b32 s12, s12, s100
	s_and_b32 s12, s12, 1
	s_cmp_eq_u32 s12, 0
	s_cbranch_scc1 .Lgbar
	s_lshl_b32 s12, 2, s8
	s_sub_i32 s12, s12, 1
	s_and_b32 s12, s12, s9
	s_bcnt1_i32_b32 s12, s12
	s_lshl_b32 s9, s12, 5
	v_readlane_b32 s8, v252, 0
	v_readlane_b32 s10, v252, 45
	v_readlane_b32 s11, v252, 46
	s_and_b32 s8, s8, 7
	s_lshl_b32 s8, s8, 6
	s_add_u32 s8, s8, 0xe3600
	s_add_u32 s10, s10, s8
	s_addc_u32 s11, s11, 0
	v_mov_b32_e32 v1, 1
	v_mov_b32_e32 v2, 0
	global_atomic_add v2, v1, s[10:11]
	s_mov_b32 s12, 0
.Llb_poll:
	global_load_dword v0, v2, s[10:11] sc1
	s_waitcnt vmcnt(0)
	v_readfirstlane_b32 s13, v0
	s_cmp_ge_u32 s13, s9
	s_cbranch_scc1 .Llb_done
	s_sleep 1
	s_add_i32 s12, s12, 1
	s_cmp_lt_u32 s12, 0x8000
	s_cbranch_scc1 .Llb_poll
.Llb_done:
	buffer_inv sc1
	s_waitcnt vmcnt(0)
	s_branch .LBB0_202
.Lgbar:
	s_add_i32 s6, 0, 0x20000
	v_mov_b32_e32 v0, s6
	s_waitcnt vmcnt(0) expcnt(0) lgkmcnt(0)
	ds_read_b32 v2, v0
	v_readlane_b32 s8, v254, 48
	s_waitcnt lgkmcnt(0)
	v_cmp_ne_u32_e32 vcc, 0, v2
	v_mov_b32_e32 v0, s8
	ds_read_b32 v0, v0
	s_cbranch_vccnz .LBB0_531
	s_mov_b32 s14, 1
	s_branch .LBB0_519

	.amdhsa_kernel _Z14fwd_megakernel4Args
		.amdhsa_group_segment_fixed_size 0
		.amdhsa_private_segment_fixed_size 0
		.amdhsa_kernarg_size 416
		.amdhsa_user_sgpr_count 2
		.amdhsa_user_sgpr_dispatch_ptr 0
		.amdhsa_user_sgpr_queue_ptr 0
		.amdhsa_user_sgpr_kernarg_segment_ptr 1
		.amdhsa_user_sgpr_dispatch_id 0
		.amdhsa_user_sgpr_kernarg_preload_length 0
		.amdhsa_user_sgpr_kernarg_preload_offset 0
		.amdhsa_user_sgpr_private_segment_size 0
		.amdhsa_uses_dynamic_stack 0
		.amdhsa_enable_private_segment 0
		.amdhsa_system_sgpr_workgroup_id_x 1
		.amdhsa_system_sgpr_workgroup_id_y 0
		.amdhsa_system_sgpr_workgroup_id_z 0
		.amdhsa_system_sgpr_workgroup_info 0
		.amdhsa_system_vgpr_workitem_id 2
		.amdhsa_next_free_vgpr 256
		.amdhsa_next_free_sgpr 101
		.amdhsa_accum_offset 256
		.amdhsa_reserve_vcc 1
		.amdhsa_float_round_mode_32 0
		.amdhsa_float_round_mode_16_64 0
		.amdhsa_float_denorm_mode_32 3
		.amdhsa_float_denorm_mode_16_64 3
		.amdhsa_dx10_clamp 1
		.amdhsa_ieee_mode 1
		.amdhsa_fp16_overflow 0
		.amdhsa_tg_split 0
		.amdhsa_exception_fp_ieee_invalid_op 0
		.amdhsa_exception_fp_denorm_src 0
		.amdhsa_exception_fp_ieee_div_zero 0
		.amdhsa_exception_fp_ieee_overflow 0
		.amdhsa_exception_fp_ieee_underflow 0
		.amdhsa_exception_fp_ieee_inexact 0
		.amdhsa_exception_int_div_zero 0
	.end_amdhsa_kernel

amdhsa.kernels:
  - .agpr_count:     0
    .args:
      - .offset:         0
        .size:           160
        .value_kind:     by_value
      - .offset:         160
        .size:           4
        .value_kind:     hidden_block_count_x
      - .offset:         164
        .size:           4
        .value_kind:     hidden_block_count_y
      - .offset:         168
        .size:           4
        .value_kind:     hidden_block_count_z
      - .offset:         172
        .size:           2
        .value_kind:     hidden_group_size_x
      - .offset:         174
        .size:           2
        .value_kind:     hidden_group_size_y
      - .offset:         176
        .size:           2
        .value_kind:     hidden_group_size_z
      - .offset:         178
        .size:           2
        .value_kind:     hidden_remainder_x
      - .offset:         180
        .size:           2
        .value_kind:     hidden_remainder_y
      - .offset:         182
        .size:           2
        .value_kind:     hidden_remainder_z
      - .offset:         200
        .size:           8
        .value_kind:     hidden_global_offset_x
      - .offset:         208
        .size:           8
        .value_kind:     hidden_global_offset_y
      - .offset:         216
        .size:           8
        .value_kind:     hidden_global_offset_z
      - .offset:         224
        .size:           2
        .value_kind:     hidden_grid_dims
      - .offset:         248
        .size:           8
        .value_kind:     hidden_multigrid_sync_arg
      - .offset:         280
        .size:           4
        .value_kind:     hidden_dynamic_lds_size
    .group_segment_fixed_size: 0
    .kernarg_segment_align: 8
    .kernarg_segment_size: 416
    .language:       OpenCL C
    .language_version:
      - 2
      - 0
    .max_flat_workgroup_size: 512
    .name:           _Z14fwd_megakernel4Args
    .private_segment_fixed_size: 0
    .sgpr_count:     107
    .sgpr_spill_count: 202
    .symbol:         _Z14fwd_megakernel4Args.kd
    .uniform_work_group_size: 1
    .uses_dynamic_stack: false
    .vgpr_count:     256
    .vgpr_spill_count: 0
    .wavefront_size: 64
